# remaining placement pads (after the FFN gate-up phase, in prep) moved into unreachable code; layout unchanged
# speedup vs baseline: 1.0029x; 1.0029x over previous
.LBB0_30:
	global_load_dword v75, v[66:67], off
	global_load_dword v76, v[68:69], off
	global_load_dword v77, v[70:71], off
	global_load_dword v78, v[72:73], off
	v_and_b32_e32 v79, 0x7e, v0
	s_add_i32 s14, 0, 0x10200
	v_lshl_or_b32 v80, v0, 2, 4
	v_lshl_add_u32 v79, v79, 2, s14
	v_add_u32_e32 v80, s14, v80
	ds_read_b32 v79, v79
	ds_read_b32 v80, v80
	v_add_co_u32_e32 v64, vcc, 0x200, v64
	s_xor_b64 s[14:15], vcc, -1
	s_and_b64 s[14:15], exec, s[14:15]
	v_add_u32_e32 v0, 64, v0
	v_lshl_add_u64 v[66:67], v[66:67], 0, s[44:45]
	v_lshl_add_u64 v[68:69], v[68:69], 0, s[44:45]
	v_lshl_add_u64 v[70:71], v[70:71], 0, s[44:45]
	v_lshl_add_u64 v[72:73], v[72:73], 0, s[44:45]
	s_or_b64 s[0:1], s[14:15], s[0:1]
	s_waitcnt vmcnt(2) lgkmcnt(0)
	v_mul_f32_e32 v81, v76, v80
	v_mul_f32_e32 v80, v75, v80
	v_fma_f32 v75, v75, v79, -v81
	v_fmac_f32_e32 v80, v76, v79
	s_waitcnt vmcnt(0)
	ds_write2st64_b32 v74, v77, v78 offset0:32 offset1:48
	ds_write2st64_b32 v74, v75, v80 offset1:16
	v_add_u32_e32 v74, 0x800, v74
	s_andn2_b64 exec, exec, s[0:1]
	s_cbranch_execnz .LBB0_30
	s_or_b64 exec, exec, s[0:1]
	s_ashr_i32 s64, s62, 5
	s_and_b32 s43, s62, 31
	s_lshl_b32 s0, s64, 9
	s_lshl_b32 s1, s43, 4
	s_or_b32 s46, s1, s0
	s_mov_b64 s[0:1], 0
	v_mov_b32_e32 v0, v88
	v_mov_b32_e32 v64, v173
	s_waitcnt lgkmcnt(0)
	s_barrier
	ds_read_b128 v[100:103], v90 offset:0
	ds_read_b128 v[104:107], v90 offset:16
	ds_read_b128 v[108:111], v90 offset:4096
	ds_read_b128 v[112:115], v90 offset:4112
	v_add_u32_e32 v78, 0, v89
	v_add_u32_e32 v79, 0x1000, v78
	ds_read2_b32 v[116:117], v78 offset0:0 offset1:16
	ds_read2_b32 v[118:119], v78 offset0:32 offset1:48
	ds_read2_b32 v[120:121], v78 offset0:64 offset1:80
	ds_read2_b32 v[122:123], v78 offset0:96 offset1:112
	ds_read2_b32 v[70:71], v79 offset0:0 offset1:16
	ds_read2_b32 v[72:73], v79 offset0:32 offset1:48
	ds_read2_b32 v[74:75], v79 offset0:64 offset1:80
	ds_read2_b32 v[76:77], v79 offset0:96 offset1:112
	s_waitcnt lgkmcnt(0)
	v_mul_f32_e32 v66, v108, v70
	v_mul_f32_e32 v68, v100, v70
	v_fma_f32 v124, v100, v116, -v66
	v_fma_f32 v125, v108, v116, v68
	v_mul_f32_e32 v66, v109, v71
	v_mul_f32_e32 v68, v101, v71
	v_fma_f32 v126, v101, v117, -v66
	v_fma_f32 v127, v109, v117, v68
	v_mul_f32_e32 v66, v110, v72
	v_mul_f32_e32 v68, v102, v72
	v_fma_f32 v128, v102, v118, -v66
	v_fma_f32 v129, v110, v118, v68
	v_mul_f32_e32 v66, v111, v73
	v_mul_f32_e32 v68, v103, v73
	v_fma_f32 v130, v103, v119, -v66
	v_fma_f32 v131, v111, v119, v68
	v_mul_f32_e32 v66, v112, v74
	v_mul_f32_e32 v68, v104, v74
	v_fma_f32 v132, v104, v120, -v66
	v_fma_f32 v133, v112, v120, v68
	v_mul_f32_e32 v66, v113, v75
	v_mul_f32_e32 v68, v105, v75
	v_fma_f32 v134, v105, v121, -v66
	v_fma_f32 v135, v113, v121, v68
	v_mul_f32_e32 v66, v114, v76
	v_mul_f32_e32 v68, v106, v76
	v_fma_f32 v136, v106, v122, -v66
	v_fma_f32 v137, v114, v122, v68
	v_mul_f32_e32 v66, v115, v77
	v_mul_f32_e32 v68, v107, v77
	v_fma_f32 v138, v107, v123, -v66
	v_fma_f32 v139, v115, v123, v68
	ds_read_b128 v[100:103], v90 offset:32
	ds_read_b128 v[104:107], v90 offset:48
	ds_read_b128 v[108:111], v90 offset:4128
	ds_read_b128 v[112:115], v90 offset:4144
	v_add_u32_e32 v78, 0x200, v89
	v_add_u32_e32 v79, 0x1000, v78
	ds_read2_b32 v[116:117], v78 offset0:0 offset1:16
	ds_read2_b32 v[118:119], v78 offset0:32 offset1:48
	ds_read2_b32 v[120:121], v78 offset0:64 offset1:80
	ds_read2_b32 v[122:123], v78 offset0:96 offset1:112
	ds_read2_b32 v[70:71], v79 offset0:0 offset1:16
	ds_read2_b32 v[72:73], v79 offset0:32 offset1:48
	ds_read2_b32 v[74:75], v79 offset0:64 offset1:80
	ds_read2_b32 v[76:77], v79 offset0:96 offset1:112
	s_waitcnt lgkmcnt(0)
	v_mul_f32_e32 v66, v108, v70
	v_mul_f32_e32 v68, v100, v70
	v_fma_f32 v140, v100, v116, -v66
	v_fma_f32 v141, v108, v116, v68
	v_mul_f32_e32 v66, v109, v71
	v_mul_f32_e32 v68, v101, v71
	v_fma_f32 v142, v101, v117, -v66
	v_fma_f32 v143, v109, v117, v68
	v_mul_f32_e32 v66, v110, v72
	v_mul_f32_e32 v68, v102, v72
	v_fma_f32 v144, v102, v118, -v66
	v_fma_f32 v145, v110, v118, v68
	v_mul_f32_e32 v66, v111, v73
	v_mul_f32_e32 v68, v103, v73
	v_fma_f32 v146, v103, v119, -v66
	v_fma_f32 v147, v111, v119, v68
	v_mul_f32_e32 v66, v112, v74
	v_mul_f32_e32 v68, v104, v74
	v_fma_f32 v148, v104, v120, -v66
	v_fma_f32 v149, v112, v120, v68
	v_mul_f32_e32 v66, v113, v75
	v_mul_f32_e32 v68, v105, v75
	v_fma_f32 v150, v105, v121, -v66
	v_fma_f32 v151, v113, v121, v68
	v_mul_f32_e32 v66, v114, v76
	v_mul_f32_e32 v68, v106, v76
	v_fma_f32 v152, v106, v122, -v66
	v_fma_f32 v80, v114, v122, v68
	v_mul_f32_e32 v66, v115, v77
	v_mul_f32_e32 v68, v107, v77
	v_fma_f32 v154, v107, v123, -v66
	v_fma_f32 v155, v115, v123, v68
	ds_read_b128 v[100:103], v90 offset:64
	ds_read_b128 v[104:107], v90 offset:80
	ds_read_b128 v[108:111], v90 offset:4160
	ds_read_b128 v[112:115], v90 offset:4176
	v_add_u32_e32 v78, 0x400, v89
	v_add_u32_e32 v79, 0x1000, v78
	ds_read2_b32 v[116:117], v78 offset0:0 offset1:16
	ds_read2_b32 v[118:119], v78 offset0:32 offset1:48
	ds_read2_b32 v[120:121], v78 offset0:64 offset1:80
	ds_read2_b32 v[122:123], v78 offset0:96 offset1:112
	ds_read2_b32 v[70:71], v79 offset0:0 offset1:16
	ds_read2_b32 v[72:73], v79 offset0:32 offset1:48
	ds_read2_b32 v[74:75], v79 offset0:64 offset1:80
	ds_read2_b32 v[76:77], v79 offset0:96 offset1:112
	s_waitcnt lgkmcnt(0)
	v_mul_f32_e32 v66, v108, v70
	v_mul_f32_e32 v68, v100, v70
	v_fma_f32 v156, v100, v116, -v66
	v_fma_f32 v157, v108, v116, v68
	v_mul_f32_e32 v66, v109, v71
	v_mul_f32_e32 v68, v101, v71
	v_fma_f32 v158, v101, v117, -v66
	v_fma_f32 v159, v109, v117, v68
	v_mul_f32_e32 v66, v110, v72
	v_mul_f32_e32 v68, v102, v72
	v_fma_f32 v160, v102, v118, -v66
	v_fma_f32 v161, v110, v118, v68
	v_mul_f32_e32 v66, v111, v73
	v_mul_f32_e32 v68, v103, v73
	v_fma_f32 v162, v103, v119, -v66
	v_fma_f32 v163, v111, v119, v68
	v_mul_f32_e32 v66, v112, v74
	v_mul_f32_e32 v68, v104, v74
	v_fma_f32 v164, v104, v120, -v66
	v_fma_f32 v165, v112, v120, v68
	v_mul_f32_e32 v66, v113, v75
	v_mul_f32_e32 v68, v105, v75
	v_fma_f32 v166, v105, v121, -v66
	v_fma_f32 v167, v113, v121, v68
	v_mul_f32_e32 v66, v114, v76
	v_mul_f32_e32 v68, v106, v76
	v_fma_f32 v168, v106, v122, -v66
	v_fma_f32 v169, v114, v122, v68
	v_mul_f32_e32 v66, v115, v77
	v_mul_f32_e32 v68, v107, v77
	v_fma_f32 v170, v107, v123, -v66
	v_fma_f32 v171, v115, v123, v68
	ds_read_b128 v[100:103], v90 offset:96
	ds_read_b128 v[104:107], v90 offset:112
	ds_read_b128 v[108:111], v90 offset:4192
	ds_read_b128 v[112:115], v90 offset:4208
	v_add_u32_e32 v78, 0x600, v89
	v_add_u32_e32 v79, 0x1000, v78
	ds_read2_b32 v[116:117], v78 offset0:0 offset1:16
	ds_read2_b32 v[118:119], v78 offset0:32 offset1:48
	ds_read2_b32 v[120:121], v78 offset0:64 offset1:80
	ds_read2_b32 v[122:123], v78 offset0:96 offset1:112
	ds_read2_b32 v[70:71], v79 offset0:0 offset1:16
	ds_read2_b32 v[72:73], v79 offset0:32 offset1:48
	ds_read2_b32 v[74:75], v79 offset0:64 offset1:80
	ds_read2_b32 v[76:77], v79 offset0:96 offset1:112
	s_waitcnt lgkmcnt(0)
	v_mul_f32_e32 v66, v108, v70
	v_mul_f32_e32 v68, v100, v70
	v_fma_f32 v172, v100, v116, -v66
	v_fma_f32 v81, v108, v116, v68
	v_mul_f32_e32 v66, v109, v71
	v_mul_f32_e32 v68, v101, v71
	v_fma_f32 v174, v101, v117, -v66
	v_fma_f32 v175, v109, v117, v68
	v_mul_f32_e32 v66, v110, v72
	v_mul_f32_e32 v68, v102, v72
	v_fma_f32 v176, v102, v118, -v66
	v_fma_f32 v177, v110, v118, v68
	v_mul_f32_e32 v66, v111, v73
	v_mul_f32_e32 v68, v103, v73
	v_fma_f32 v178, v103, v119, -v66
	v_fma_f32 v179, v111, v119, v68
	v_mul_f32_e32 v66, v112, v74
	v_mul_f32_e32 v68, v104, v74
	v_fma_f32 v180, v104, v120, -v66
	v_fma_f32 v181, v112, v120, v68
	v_mul_f32_e32 v66, v113, v75
	v_mul_f32_e32 v68, v105, v75
	v_fma_f32 v182, v105, v121, -v66
	v_fma_f32 v183, v113, v121, v68
	v_mul_f32_e32 v66, v114, v76
	v_mul_f32_e32 v68, v106, v76
	v_fma_f32 v184, v106, v122, -v66
	v_fma_f32 v185, v114, v122, v68
	v_mul_f32_e32 v66, v115, v77
	v_mul_f32_e32 v68, v107, v77
	v_fma_f32 v186, v107, v123, -v66
	v_fma_f32 v187, v115, v123, v68
	ds_read_b128 v[100:103], v90 offset:128
	ds_read_b128 v[104:107], v90 offset:144
	ds_read_b128 v[108:111], v90 offset:4224
	ds_read_b128 v[112:115], v90 offset:4240
	v_add_u32_e32 v78, 0x800, v89
	v_add_u32_e32 v79, 0x1000, v78
	ds_read2_b32 v[116:117], v78 offset0:0 offset1:16
	ds_read2_b32 v[118:119], v78 offset0:32 offset1:48
	ds_read2_b32 v[120:121], v78 offset0:64 offset1:80
	ds_read2_b32 v[122:123], v78 offset0:96 offset1:112
	ds_read2_b32 v[70:71], v79 offset0:0 offset1:16
	ds_read2_b32 v[72:73], v79 offset0:32 offset1:48
	ds_read2_b32 v[74:75], v79 offset0:64 offset1:80
	ds_read2_b32 v[76:77], v79 offset0:96 offset1:112
	s_waitcnt lgkmcnt(0)
	v_mul_f32_e32 v66, v108, v70
	v_mul_f32_e32 v68, v100, v70
	v_fma_f32 v188, v100, v116, -v66
	v_fma_f32 v189, v108, v116, v68
	v_mul_f32_e32 v66, v109, v71
	v_mul_f32_e32 v68, v101, v71
	v_fma_f32 v190, v101, v117, -v66
	v_fma_f32 v191, v109, v117, v68
	v_mul_f32_e32 v66, v110, v72
	v_mul_f32_e32 v68, v102, v72
	v_fma_f32 v192, v102, v118, -v66
	v_fma_f32 v193, v110, v118, v68
	v_mul_f32_e32 v66, v111, v73
	v_mul_f32_e32 v68, v103, v73
	v_fma_f32 v194, v103, v119, -v66
	v_fma_f32 v195, v111, v119, v68
	v_mul_f32_e32 v66, v112, v74
	v_mul_f32_e32 v68, v104, v74
	v_fma_f32 v196, v104, v120, -v66
	v_fma_f32 v197, v112, v120, v68
	v_mul_f32_e32 v66, v113, v75
	v_mul_f32_e32 v68, v105, v75
	v_fma_f32 v198, v105, v121, -v66
	v_fma_f32 v199, v113, v121, v68
	v_mul_f32_e32 v66, v114, v76
	v_mul_f32_e32 v68, v106, v76
	v_fma_f32 v200, v106, v122, -v66
	v_fma_f32 v201, v114, v122, v68
	v_mul_f32_e32 v66, v115, v77
	v_mul_f32_e32 v68, v107, v77
	v_fma_f32 v202, v107, v123, -v66
	v_fma_f32 v203, v115, v123, v68
	ds_read_b128 v[100:103], v90 offset:160
	ds_read_b128 v[104:107], v90 offset:176
	ds_read_b128 v[108:111], v90 offset:4256
	ds_read_b128 v[112:115], v90 offset:4272
	v_add_u32_e32 v78, 0xa00, v89
	v_add_u32_e32 v79, 0x1000, v78
	ds_read2_b32 v[116:117], v78 offset0:0 offset1:16
	ds_read2_b32 v[118:119], v78 offset0:32 offset1:48
	ds_read2_b32 v[120:121], v78 offset0:64 offset1:80
	ds_read2_b32 v[122:123], v78 offset0:96 offset1:112
	ds_read2_b32 v[70:71], v79 offset0:0 offset1:16
	ds_read2_b32 v[72:73], v79 offset0:32 offset1:48
	ds_read2_b32 v[74:75], v79 offset0:64 offset1:80
	ds_read2_b32 v[76:77], v79 offset0:96 offset1:112
	s_waitcnt lgkmcnt(0)
	v_mul_f32_e32 v66, v108, v70
	v_mul_f32_e32 v68, v100, v70
	v_fma_f32 v204, v100, v116, -v66
	v_fma_f32 v205, v108, v116, v68
	v_mul_f32_e32 v66, v109, v71
	v_mul_f32_e32 v68, v101, v71
	v_fma_f32 v206, v101, v117, -v66
	v_fma_f32 v207, v109, v117, v68
	v_mul_f32_e32 v66, v110, v72
	v_mul_f32_e32 v68, v102, v72
	v_fma_f32 v208, v102, v118, -v66
	v_fma_f32 v209, v110, v118, v68
	v_mul_f32_e32 v66, v111, v73
	v_mul_f32_e32 v68, v103, v73
	v_fma_f32 v210, v103, v119, -v66
	v_fma_f32 v211, v111, v119, v68
	v_mul_f32_e32 v66, v112, v74
	v_mul_f32_e32 v68, v104, v74
	v_fma_f32 v212, v104, v120, -v66
	v_fma_f32 v213, v112, v120, v68
	v_mul_f32_e32 v66, v113, v75
	v_mul_f32_e32 v68, v105, v75
	v_fma_f32 v214, v105, v121, -v66
	v_fma_f32 v215, v113, v121, v68
	v_mul_f32_e32 v66, v114, v76
	v_mul_f32_e32 v68, v106, v76
	v_fma_f32 v216, v106, v122, -v66
	v_fma_f32 v217, v114, v122, v68
	v_mul_f32_e32 v66, v115, v77
	v_mul_f32_e32 v68, v107, v77
	v_fma_f32 v218, v107, v123, -v66
	v_fma_f32 v219, v115, v123, v68
	ds_read_b128 v[100:103], v90 offset:192
	ds_read_b128 v[104:107], v90 offset:208
	ds_read_b128 v[108:111], v90 offset:4288
	ds_read_b128 v[112:115], v90 offset:4304
	v_add_u32_e32 v78, 0xc00, v89
	v_add_u32_e32 v79, 0x1000, v78
	ds_read2_b32 v[116:117], v78 offset0:0 offset1:16
	ds_read2_b32 v[118:119], v78 offset0:32 offset1:48
	ds_read2_b32 v[120:121], v78 offset0:64 offset1:80
	ds_read2_b32 v[122:123], v78 offset0:96 offset1:112
	ds_read2_b32 v[70:71], v79 offset0:0 offset1:16
	ds_read2_b32 v[72:73], v79 offset0:32 offset1:48
	ds_read2_b32 v[74:75], v79 offset0:64 offset1:80
	ds_read2_b32 v[76:77], v79 offset0:96 offset1:112
	s_waitcnt lgkmcnt(0)
	v_mul_f32_e32 v66, v108, v70
	v_mul_f32_e32 v68, v100, v70
	v_fma_f32 v220, v100, v116, -v66
	v_fma_f32 v221, v108, v116, v68
	v_mul_f32_e32 v66, v109, v71
	v_mul_f32_e32 v68, v101, v71
	v_fma_f32 v222, v101, v117, -v66
	v_fma_f32 v223, v109, v117, v68
	v_mul_f32_e32 v66, v110, v72
	v_mul_f32_e32 v68, v102, v72
	v_fma_f32 v224, v102, v118, -v66
	v_fma_f32 v225, v110, v118, v68
	v_mul_f32_e32 v66, v111, v73
	v_mul_f32_e32 v68, v103, v73
	v_fma_f32 v226, v103, v119, -v66
	v_fma_f32 v227, v111, v119, v68
	v_mul_f32_e32 v66, v112, v74
	v_mul_f32_e32 v68, v104, v74
	v_fma_f32 v228, v104, v120, -v66
	v_fma_f32 v229, v112, v120, v68
	v_mul_f32_e32 v66, v113, v75
	v_mul_f32_e32 v68, v105, v75
	v_fma_f32 v230, v105, v121, -v66
	v_fma_f32 v231, v113, v121, v68
	v_mul_f32_e32 v66, v114, v76
	v_mul_f32_e32 v68, v106, v76
	v_fma_f32 v232, v106, v122, -v66
	v_fma_f32 v233, v114, v122, v68
	v_mul_f32_e32 v66, v115, v77
	v_mul_f32_e32 v68, v107, v77
	v_fma_f32 v234, v107, v123, -v66
	v_fma_f32 v235, v115, v123, v68
	ds_read_b128 v[100:103], v90 offset:224
	ds_read_b128 v[104:107], v90 offset:240
	ds_read_b128 v[108:111], v90 offset:4320
	ds_read_b128 v[112:115], v90 offset:4336
	v_add_u32_e32 v78, 0xe00, v89
	v_add_u32_e32 v79, 0x1000, v78
	ds_read2_b32 v[116:117], v78 offset0:0 offset1:16
	ds_read2_b32 v[118:119], v78 offset0:32 offset1:48
	ds_read2_b32 v[120:121], v78 offset0:64 offset1:80
	ds_read2_b32 v[122:123], v78 offset0:96 offset1:112
	ds_read2_b32 v[70:71], v79 offset0:0 offset1:16
	ds_read2_b32 v[72:73], v79 offset0:32 offset1:48
	ds_read2_b32 v[74:75], v79 offset0:64 offset1:80
	ds_read2_b32 v[76:77], v79 offset0:96 offset1:112
	s_waitcnt lgkmcnt(0)
	v_mul_f32_e32 v66, v108, v70
	v_mul_f32_e32 v68, v100, v70
	v_fma_f32 v236, v100, v116, -v66
	v_fma_f32 v237, v108, v116, v68
	v_mul_f32_e32 v66, v109, v71
	v_mul_f32_e32 v68, v101, v71
	v_fma_f32 v238, v101, v117, -v66
	v_fma_f32 v239, v109, v117, v68
	v_mul_f32_e32 v66, v110, v72
	v_mul_f32_e32 v68, v102, v72
	v_fma_f32 v240, v102, v118, -v66
	v_fma_f32 v241, v110, v118, v68
	v_mul_f32_e32 v66, v111, v73
	v_mul_f32_e32 v68, v103, v73
	v_fma_f32 v242, v103, v119, -v66
	v_fma_f32 v243, v111, v119, v68
	v_mul_f32_e32 v66, v112, v74
	v_mul_f32_e32 v68, v104, v74
	v_fma_f32 v244, v104, v120, -v66
	v_fma_f32 v245, v112, v120, v68
	v_mul_f32_e32 v66, v113, v75
	v_mul_f32_e32 v68, v105, v75
	v_fma_f32 v246, v105, v121, -v66
	v_fma_f32 v247, v113, v121, v68
	v_mul_f32_e32 v66, v114, v76
	v_mul_f32_e32 v68, v106, v76
	v_fma_f32 v248, v106, v122, -v66
	v_fma_f32 v249, v114, v122, v68
	v_mul_f32_e32 v66, v115, v77
	v_mul_f32_e32 v68, v107, v77
	v_fma_f32 v250, v107, v123, -v66
	v_fma_f32 v251, v115, v123, v68
	s_branch .LBB0_33
	s_nop 0
	s_nop 0
	s_nop 0
	s_nop 0
	s_nop 0
	s_nop 0
	s_nop 0
	s_nop 0
	s_nop 0
	s_nop 0
	s_nop 0
	s_nop 0
	s_nop 0
	s_nop 0
	s_nop 0
	s_nop 0
	s_nop 0
	s_nop 0
	s_nop 0
	s_nop 0
	s_nop 0
	s_nop 0
	s_nop 0
	s_nop 0
	s_nop 0
	s_nop 0
	s_nop 0
	s_nop 0
	s_nop 0
	s_nop 0
	s_nop 0
	s_nop 0
	s_nop 0
	s_nop 0
	s_nop 0
	s_nop 0
	s_nop 0
	s_nop 0
	s_nop 0
	s_nop 0
	s_nop 0
	s_nop 0

.LBB0_1068:
	s_lshl_b32 s9, s54, 8
	s_add_i32 s9, s9, s27
	v_or_b32_e32 v154, s9, v157
	v_ashrrev_i32_e32 v155, 31, v154
	v_or_b32_e32 v150, 16, v154
	v_lshlrev_b64 v[146:147], 6, v[154:155]
	v_ashrrev_i32_e32 v151, 31, v150
	v_or_b32_e32 v158, 32, v154
	v_lshl_add_u64 v[146:147], v[136:137], 0, v[146:147]
	v_lshlrev_b64 v[150:151], 6, v[150:151]
	v_ashrrev_i32_e32 v159, 31, v158
	global_load_dwordx4 v[146:149], v[146:147], off
	v_lshl_add_u64 v[150:151], v[136:137], 0, v[150:151]
	v_lshlrev_b64 v[158:159], 6, v[158:159]
	global_load_dwordx4 v[150:153], v[150:151], off
	v_lshl_add_u64 v[158:159], v[136:137], 0, v[158:159]
	global_load_dwordx4 v[178:181], v[158:159], off
	v_or_b32_e32 v158, 48, v154
	v_ashrrev_i32_e32 v159, 31, v158
	v_lshlrev_b64 v[158:159], 6, v[158:159]
	v_lshl_add_u64 v[158:159], v[136:137], 0, v[158:159]
	global_load_dwordx4 v[190:193], v[158:159], off
	v_add_u32_e32 v158, 0x80, v154
	v_ashrrev_i32_e32 v159, 31, v158
	v_lshlrev_b64 v[158:159], 6, v[158:159]
	v_lshl_add_u64 v[158:159], v[136:137], 0, v[158:159]
	global_load_dwordx4 v[194:197], v[158:159], off
	v_add_u32_e32 v158, 0x90, v154
	v_ashrrev_i32_e32 v159, 31, v158
	v_lshlrev_b64 v[158:159], 6, v[158:159]
	v_lshl_add_u64 v[158:159], v[136:137], 0, v[158:159]
	global_load_dwordx4 v[198:201], v[158:159], off
	v_add_u32_e32 v158, 0xa0, v154
	v_add_u32_e32 v154, 0xb0, v154
	v_ashrrev_i32_e32 v159, 31, v158
	v_ashrrev_i32_e32 v155, 31, v154
	v_lshlrev_b64 v[158:159], 6, v[158:159]
	v_lshlrev_b64 v[154:155], 6, v[154:155]
	v_lshl_add_u64 v[158:159], v[136:137], 0, v[158:159]
	v_lshl_add_u64 v[154:155], v[136:137], 0, v[154:155]
	global_load_dwordx4 v[202:205], v[158:159], off
	global_load_dwordx4 v[206:209], v[154:155], off
	v_and_b32_e32 v156, 64, v213
	v_xor_b32_e32 v145, 16, v213
	v_add_u32_e32 v156, 64, v156
	v_cmp_lt_i32_e32 vcc, v145, v156
	s_mov_b64 s[56:57], s[44:45]
	s_mov_b32 s55, s72
	v_cndmask_b32_e32 v145, v213, v145, vcc
	v_lshlrev_b32_e32 v165, 2, v145
	v_xor_b32_e32 v145, 32, v213
	v_cmp_lt_i32_e32 vcc, v145, v156
	s_waitcnt vmcnt(0)
	v_mov_b32_e32 v154, v147
	v_mov_b32_e32 v155, v148
	v_mov_b32_e32 v147, v149
	v_pk_add_f32 v[162:163], v[154:155], v[146:147]
	v_mov_b32_e32 v146, v151
	v_mov_b32_e32 v147, v152
	v_mov_b32_e32 v151, v153
	v_pk_add_f32 v[166:167], v[146:147], v[150:151]
	v_mov_b32_e32 v146, v179
	v_mov_b32_e32 v147, v180
	v_mov_b32_e32 v179, v181
	v_pk_add_f32 v[154:155], v[146:147], v[178:179]
	v_mov_b32_e32 v178, v166
	v_mov_b32_e32 v179, v162
	v_mov_b32_e32 v162, v167
	v_pk_add_f32 v[162:163], v[178:179], v[162:163]
	ds_bpermute_b32 v167, v165, v163
	ds_bpermute_b32 v166, v165, v162
	v_cndmask_b32_e32 v145, v213, v145, vcc
	v_lshlrev_b32_e32 v145, 2, v145
	v_mov_b32_e32 v146, v191
	v_mov_b32_e32 v147, v192
	s_waitcnt lgkmcnt(0)
	v_pk_add_f32 v[162:163], v[162:163], v[166:167]
	ds_bpermute_b32 v167, v145, v163
	ds_bpermute_b32 v166, v145, v162
	v_mov_b32_e32 v191, v193
	v_pk_add_f32 v[158:159], v[146:147], v[190:191]
	v_mov_b32_e32 v146, v195
	v_mov_b32_e32 v147, v196
	s_waitcnt lgkmcnt(0)
	v_pk_add_f32 v[166:167], v[162:163], v[166:167]
	v_mov_b64_e32 v[162:163], s[64:65]
	v_pk_fma_f32 v[166:167], v[166:167], s[28:29], v[162:163] op_sel_hi:[1,0,0]
	v_mov_b32_e32 v195, v197
	v_mul_f32_e32 v156, 0x4b800000, v167
	v_cmp_gt_f32_e64 s[0:1], s52, v167
	v_cmp_gt_f32_e32 vcc, s52, v166
	v_pk_add_f32 v[150:151], v[146:147], v[194:195]
	v_cndmask_b32_e64 v156, v167, v156, s[0:1]
	v_rsq_f32_e32 v156, v156
	v_mov_b32_e32 v146, v199
	v_mov_b32_e32 v147, v200
	v_mov_b32_e32 v199, v201
	v_mul_f32_e32 v160, 0x45800000, v156
	v_cndmask_b32_e64 v160, v156, v160, s[0:1]
	v_mul_f32_e32 v156, 0x4b800000, v166
	v_cndmask_b32_e32 v156, v166, v156, vcc
	v_rsq_f32_e32 v156, v156
	v_pk_add_f32 v[152:153], v[146:147], v[198:199]
	v_mov_b32_e32 v146, v203
	v_mov_b32_e32 v147, v204
	v_mul_f32_e32 v166, 0x45800000, v156
	v_mov_b32_e32 v203, v205
	v_mov_b32_e32 v148, v207
	v_mov_b32_e32 v149, v208
	v_mov_b32_e32 v207, v209
	v_cndmask_b32_e32 v156, v156, v166, vcc
	v_mov_b32_e32 v166, v158
	v_mov_b32_e32 v167, v154
	v_mov_b32_e32 v154, v159
	v_pk_add_f32 v[146:147], v[146:147], v[202:203]
	v_pk_add_f32 v[148:149], v[148:149], v[206:207]
	v_pk_add_f32 v[154:155], v[166:167], v[154:155]
	v_mov_b32_e32 v166, v152
	v_mov_b32_e32 v167, v150
	v_mov_b32_e32 v150, v153
	v_pk_add_f32 v[150:151], v[166:167], v[150:151]
	v_mov_b32_e32 v166, v148
	v_mov_b32_e32 v167, v146
	v_mov_b32_e32 v146, v149
	v_pk_add_f32 v[146:147], v[166:167], v[146:147]
	ds_bpermute_b32 v159, v165, v155
	ds_bpermute_b32 v158, v165, v154
	ds_bpermute_b32 v153, v165, v151
	ds_bpermute_b32 v152, v165, v150
	ds_bpermute_b32 v149, v165, v147
	ds_bpermute_b32 v148, v165, v146
	s_waitcnt lgkmcnt(4)
	v_pk_add_f32 v[154:155], v[154:155], v[158:159]
	ds_bpermute_b32 v159, v145, v155
	s_waitcnt lgkmcnt(3)
	v_pk_add_f32 v[150:151], v[150:151], v[152:153]
	ds_bpermute_b32 v158, v145, v154
	s_waitcnt lgkmcnt(2)
	v_pk_add_f32 v[146:147], v[146:147], v[148:149]
	ds_bpermute_b32 v153, v145, v151
	ds_bpermute_b32 v152, v145, v150
	ds_bpermute_b32 v149, v145, v147
	ds_bpermute_b32 v148, v145, v146
	s_waitcnt lgkmcnt(4)
	v_pk_add_f32 v[154:155], v[154:155], v[158:159]
	s_waitcnt lgkmcnt(2)
	v_pk_add_f32 v[150:151], v[150:151], v[152:153]
	v_pk_fma_f32 v[154:155], v[154:155], s[28:29], v[162:163] op_sel_hi:[1,0,0]
	s_waitcnt lgkmcnt(0)
	v_pk_add_f32 v[146:147], v[146:147], v[148:149]
	v_pk_fma_f32 v[150:151], v[150:151], s[28:29], v[162:163] op_sel_hi:[1,0,0]
	v_pk_fma_f32 v[146:147], v[146:147], s[28:29], v[162:163] op_sel_hi:[1,0,0]
	v_mul_f32_e32 v158, 0x4b800000, v155
	v_cmp_gt_f32_e64 s[0:1], s52, v155
	v_mul_f32_e32 v152, 0x4b800000, v151
	s_nop 0
	v_cndmask_b32_e64 v155, v155, v158, s[0:1]
	v_rsq_f32_e32 v155, v155
	v_mul_f32_e32 v145, 0x4b800000, v147
	v_mul_f32_e32 v158, 0x45800000, v155
	v_cndmask_b32_e64 v158, v155, v158, s[0:1]
	v_cmp_gt_f32_e64 s[0:1], s52, v151
	v_cmp_gt_f32_e32 vcc, s52, v154
	s_nop 0
	v_cndmask_b32_e64 v151, v151, v152, s[0:1]
	v_rsq_f32_e32 v151, v151
	v_mul_f32_e32 v155, 0x4b800000, v154
	v_mul_f32_e32 v152, 0x45800000, v151
	v_cndmask_b32_e64 v152, v151, v152, s[0:1]
	v_cmp_gt_f32_e64 s[0:1], s52, v147
	s_nop 1
	v_cndmask_b32_e64 v145, v147, v145, s[0:1]
	v_rsq_f32_e32 v145, v145
	v_cndmask_b32_e32 v154, v154, v155, vcc
	v_mul_f32_e32 v236, 0xbfb8aa3b, v160
	v_mul_f32_e32 v237, v160, v160
	v_rcp_f32_e32 v237, v237
	v_mul_f32_e32 v220, v236, v124
	v_mul_f32_e32 v222, v236, v125
	v_mul_f32_e32 v224, v236, v126
	v_mul_f32_e32 v226, v236, v127
	v_mul_f32_e32 v221, v124, v120
	v_mul_f32_e32 v223, v125, v121
	v_mul_f32_e32 v225, v126, v122
	v_mul_f32_e32 v227, v127, v123
	v_exp_f32_e32 v220, v220
	v_exp_f32_e32 v222, v222
	v_exp_f32_e32 v224, v224
	v_exp_f32_e32 v226, v226
	v_fma_f32 v220, v220, v237, v237
	v_fma_f32 v222, v222, v237, v237
	v_fma_f32 v224, v224, v237, v237
	v_fma_f32 v226, v226, v237, v237
	v_rcp_f32_e32 v220, v220
	v_rcp_f32_e32 v222, v222
	v_rcp_f32_e32 v224, v224
	v_rcp_f32_e32 v226, v226
	v_mul_f32_e32 v124, v221, v220
	v_mul_f32_e32 v125, v223, v222
	v_mul_f32_e32 v126, v225, v224
	v_mul_f32_e32 v122, v227, v226
	v_mul_f32_e32 v147, 0x45800000, v145
	v_cndmask_b32_e64 v148, v145, v147, s[0:1]
	s_lshl_b32 s0, s36, 7
	s_or_b32 s0, s0, s34
	s_ashr_i32 s11, s0, 6
	s_ashr_i32 s0, s9, 8
	s_mul_i32 s0, s0, 44
	s_add_i32 s0, s0, s11
	s_lshl_b32 s0, s0, 1
	s_or_b32 s0, s0, s87
	s_ashr_i32 s1, s0, 31
	s_lshl_b64 s[0:1], s[0:1], 14
	v_rsq_f32_e32 v154, v154
	s_nop 0
	v_mul_f32_e32 v155, 0x45800000, v154
	v_cndmask_b32_e32 v154, v154, v155, vcc
	v_cmp_gt_f32_e32 vcc, s52, v150
	v_mul_f32_e32 v151, 0x4b800000, v150
	s_nop 0
	v_cndmask_b32_e32 v150, v150, v151, vcc
	v_rsq_f32_e32 v150, v150
	s_addk_i32 s9, 0x80
	v_mul_f32_e32 v151, 0x45800000, v150
	v_cndmask_b32_e32 v150, v150, v151, vcc
	v_cmp_gt_f32_e32 vcc, s52, v146
	v_mul_f32_e32 v145, 0x4b800000, v146
	s_nop 0
	v_cndmask_b32_e32 v145, v146, v145, vcc
	v_rsq_f32_e32 v145, v145
	v_mul_f32_e32 v228, v236, v116
	v_mul_f32_e32 v230, v236, v117
	v_mul_f32_e32 v232, v236, v118
	v_mul_f32_e32 v234, v236, v119
	v_mul_f32_e32 v229, v116, v112
	v_mul_f32_e32 v231, v117, v113
	v_mul_f32_e32 v233, v118, v114
	v_mul_f32_e32 v235, v119, v115
	v_exp_f32_e32 v228, v228
	v_exp_f32_e32 v230, v230
	v_exp_f32_e32 v232, v232
	v_exp_f32_e32 v234, v234
	v_fma_f32 v228, v228, v237, v237
	v_fma_f32 v230, v230, v237, v237
	v_fma_f32 v232, v232, v237, v237
	v_fma_f32 v234, v234, v237, v237
	v_rcp_f32_e32 v228, v228
	v_rcp_f32_e32 v230, v230
	v_rcp_f32_e32 v232, v232
	v_rcp_f32_e32 v234, v234
	v_mul_f32_e32 v116, v229, v228
	v_mul_f32_e32 v117, v231, v230
	v_mul_f32_e32 v118, v233, v232
	v_mul_f32_e32 v112, v235, v234
	v_cvt_pk_bf16_f32 v114, v124, v125
	v_cvt_pk_bf16_f32 v115, v126, v122
	v_cvt_pk_bf16_f32 v116, v116, v117
	v_mul_f32_e32 v146, 0x45800000, v145
	v_cndmask_b32_e32 v146, v145, v146, vcc
	v_mov_b32_e32 v145, v169
	v_cvt_pk_bf16_f32 v117, v118, v112
	v_lshl_add_u64 v[112:113], v[138:139], 0, s[0:1]
	global_store_dwordx4 v[112:113], v[114:117], off
	s_ashr_i32 s0, s9, 8
	s_mul_i32 s0, s0, 44
	s_add_i32 s0, s0, s11
	s_lshl_b32 s0, s0, 1
	s_or_b32 s0, s0, s87
	s_ashr_i32 s1, s0, 31
	s_and_b32 s9, s9, 0xc0
	s_lshl_b64 s[0:1], s[0:1], 14
	s_add_u32 s0, s48, s0
	s_addc_u32 s1, s49, s1
	s_andn2_b64 vcc, exec, s[2:3]
	v_mul_f32_e32 v238, 0xbfb8aa3b, v156
	v_mul_f32_e32 v239, v156, v156
	v_rcp_f32_e32 v239, v239
	v_mul_f32_e32 v220, v238, v108
	v_mul_f32_e32 v222, v238, v109
	v_mul_f32_e32 v224, v238, v110
	v_mul_f32_e32 v226, v238, v111
	v_mul_f32_e32 v221, v108, v104
	v_mul_f32_e32 v223, v109, v105
	v_mul_f32_e32 v225, v110, v106
	v_mul_f32_e32 v227, v111, v107
	v_exp_f32_e32 v220, v220
	v_exp_f32_e32 v222, v222
	v_exp_f32_e32 v224, v224
	v_exp_f32_e32 v226, v226
	v_fma_f32 v220, v220, v239, v239
	v_fma_f32 v222, v222, v239, v239
	v_fma_f32 v224, v224, v239, v239
	v_fma_f32 v226, v226, v239, v239
	v_rcp_f32_e32 v220, v220
	v_rcp_f32_e32 v222, v222
	v_rcp_f32_e32 v224, v224
	v_rcp_f32_e32 v226, v226
	v_mul_f32_e32 v108, v221, v220
	v_mul_f32_e32 v109, v223, v222
	v_mul_f32_e32 v110, v225, v224
	v_mul_f32_e32 v106, v227, v226
	v_mul_f32_e32 v228, v238, v100
	v_mul_f32_e32 v230, v238, v101
	v_mul_f32_e32 v232, v238, v102
	v_mul_f32_e32 v234, v238, v103
	v_mul_f32_e32 v229, v100, v96
	v_mul_f32_e32 v231, v101, v97
	v_mul_f32_e32 v233, v102, v98
	v_mul_f32_e32 v235, v103, v99
	v_exp_f32_e32 v228, v228
	v_exp_f32_e32 v230, v230
	v_exp_f32_e32 v232, v232
	v_exp_f32_e32 v234, v234
	v_fma_f32 v228, v228, v239, v239
	v_fma_f32 v230, v230, v239, v239
	v_fma_f32 v232, v232, v239, v239
	v_fma_f32 v234, v234, v239, v239
	v_rcp_f32_e32 v228, v228
	v_rcp_f32_e32 v230, v230
	v_rcp_f32_e32 v232, v232
	v_rcp_f32_e32 v234, v234
	v_mul_f32_e32 v100, v229, v228
	v_mul_f32_e32 v101, v231, v230
	v_mul_f32_e32 v102, v233, v232
	v_mul_f32_e32 v99, v235, v234
	v_cvt_pk_bf16_f32 v96, v108, v109
	v_cvt_pk_bf16_f32 v97, v110, v106
	v_cvt_pk_bf16_f32 v98, v100, v101
	v_cvt_pk_bf16_f32 v99, v102, v99
	global_store_dwordx4 v[112:113], v[96:99], off offset:1024
	s_nop 1
	v_mul_f32_e32 v240, 0xbfb8aa3b, v158
	v_mul_f32_e32 v241, v158, v158
	v_rcp_f32_e32 v241, v241
	v_mul_f32_e32 v220, v240, v92
	v_mul_f32_e32 v222, v240, v93
	v_mul_f32_e32 v224, v240, v94
	v_mul_f32_e32 v226, v240, v95
	v_mul_f32_e32 v221, v92, v88
	v_mul_f32_e32 v223, v93, v89
	v_mul_f32_e32 v225, v94, v90
	v_mul_f32_e32 v227, v95, v91
	v_exp_f32_e32 v220, v220
	v_exp_f32_e32 v222, v222
	v_exp_f32_e32 v224, v224
	v_exp_f32_e32 v226, v226
	v_fma_f32 v220, v220, v241, v241
	v_fma_f32 v222, v222, v241, v241
	v_fma_f32 v224, v224, v241, v241
	v_fma_f32 v226, v226, v241, v241
	v_rcp_f32_e32 v220, v220
	v_rcp_f32_e32 v222, v222
	v_rcp_f32_e32 v224, v224
	v_rcp_f32_e32 v226, v226
	v_mul_f32_e32 v92, v221, v220
	v_mul_f32_e32 v93, v223, v222
	v_mul_f32_e32 v94, v225, v224
	v_mul_f32_e32 v90, v227, v226
	v_mul_f32_e32 v228, v240, v84
	v_mul_f32_e32 v230, v240, v85
	v_mul_f32_e32 v232, v240, v86
	v_mul_f32_e32 v234, v240, v87
	v_mul_f32_e32 v229, v84, v80
	v_mul_f32_e32 v231, v85, v81
	v_mul_f32_e32 v233, v86, v82
	v_mul_f32_e32 v235, v87, v83
	v_exp_f32_e32 v228, v228
	v_exp_f32_e32 v230, v230
	v_exp_f32_e32 v232, v232
	v_exp_f32_e32 v234, v234
	v_fma_f32 v228, v228, v241, v241
	v_fma_f32 v230, v230, v241, v241
	v_fma_f32 v232, v232, v241, v241
	v_fma_f32 v234, v234, v241, v241
	v_rcp_f32_e32 v228, v228
	v_rcp_f32_e32 v230, v230
	v_rcp_f32_e32 v232, v232
	v_rcp_f32_e32 v234, v234
	v_mul_f32_e32 v84, v229, v228
	v_mul_f32_e32 v85, v231, v230
	v_mul_f32_e32 v86, v233, v232
	v_mul_f32_e32 v83, v235, v234
	v_cvt_pk_bf16_f32 v80, v92, v93
	v_cvt_pk_bf16_f32 v81, v94, v90
	v_cvt_pk_bf16_f32 v82, v84, v85
	v_cvt_pk_bf16_f32 v83, v86, v83
	global_store_dwordx4 v[112:113], v[80:83], off offset:2048
	s_nop 1
	v_mul_f32_e32 v242, 0xbfb8aa3b, v154
	v_mul_f32_e32 v243, v154, v154
	v_rcp_f32_e32 v243, v243
	v_mul_f32_e32 v220, v242, v76
	v_mul_f32_e32 v222, v242, v77
	v_mul_f32_e32 v224, v242, v78
	v_mul_f32_e32 v226, v242, v79
	v_mul_f32_e32 v221, v76, v72
	v_mul_f32_e32 v223, v77, v73
	v_mul_f32_e32 v225, v78, v74
	v_mul_f32_e32 v227, v79, v75
	v_exp_f32_e32 v220, v220
	v_exp_f32_e32 v222, v222
	v_exp_f32_e32 v224, v224
	v_exp_f32_e32 v226, v226
	v_fma_f32 v220, v220, v243, v243
	v_fma_f32 v222, v222, v243, v243
	v_fma_f32 v224, v224, v243, v243
	v_fma_f32 v226, v226, v243, v243
	v_rcp_f32_e32 v220, v220
	v_rcp_f32_e32 v222, v222
	v_rcp_f32_e32 v224, v224
	v_rcp_f32_e32 v226, v226
	v_mul_f32_e32 v76, v221, v220
	v_mul_f32_e32 v77, v223, v222
	v_mul_f32_e32 v78, v225, v224
	v_mul_f32_e32 v74, v227, v226
	v_mul_f32_e32 v228, v242, v68
	v_mul_f32_e32 v230, v242, v69
	v_mul_f32_e32 v232, v242, v70
	v_mul_f32_e32 v234, v242, v71
	v_mul_f32_e32 v229, v68, v64
	v_mul_f32_e32 v231, v69, v65
	v_mul_f32_e32 v233, v70, v66
	v_mul_f32_e32 v235, v71, v67
	v_exp_f32_e32 v228, v228
	v_exp_f32_e32 v230, v230
	v_exp_f32_e32 v232, v232
	v_exp_f32_e32 v234, v234
	v_fma_f32 v228, v228, v243, v243
	v_fma_f32 v230, v230, v243, v243
	v_fma_f32 v232, v232, v243, v243
	v_fma_f32 v234, v234, v243, v243
	v_rcp_f32_e32 v228, v228
	v_rcp_f32_e32 v230, v230
	v_rcp_f32_e32 v232, v232
	v_rcp_f32_e32 v234, v234
	v_mul_f32_e32 v68, v229, v228
	v_mul_f32_e32 v69, v231, v230
	v_mul_f32_e32 v70, v233, v232
	v_mul_f32_e32 v67, v235, v234
	v_cvt_pk_bf16_f32 v64, v76, v77
	v_cvt_pk_bf16_f32 v65, v78, v74
	v_cvt_pk_bf16_f32 v66, v68, v69
	v_cvt_pk_bf16_f32 v67, v70, v67
	global_store_dwordx4 v[112:113], v[64:67], off offset:3072
	s_nop 1
	v_or_b32_e32 v66, s9, v157
	v_lshlrev_b32_e32 v168, 6, v66
	v_mul_f32_e32 v244, 0xbfb8aa3b, v152
	v_mul_f32_e32 v245, v152, v152
	v_rcp_f32_e32 v245, v245
	v_mul_f32_e32 v220, v244, v60
	v_mul_f32_e32 v222, v244, v61
	v_mul_f32_e32 v224, v244, v62
	v_mul_f32_e32 v226, v244, v63
	v_mul_f32_e32 v221, v60, v56
	v_mul_f32_e32 v223, v61, v57
	v_mul_f32_e32 v225, v62, v58
	v_mul_f32_e32 v227, v63, v59
	v_exp_f32_e32 v220, v220
	v_exp_f32_e32 v222, v222
	v_exp_f32_e32 v224, v224
	v_exp_f32_e32 v226, v226
	v_fma_f32 v220, v220, v245, v245
	v_fma_f32 v222, v222, v245, v245
	v_fma_f32 v224, v224, v245, v245
	v_fma_f32 v226, v226, v245, v245
	v_rcp_f32_e32 v220, v220
	v_rcp_f32_e32 v222, v222
	v_rcp_f32_e32 v224, v224
	v_rcp_f32_e32 v226, v226
	v_mul_f32_e32 v60, v221, v220
	v_mul_f32_e32 v61, v223, v222
	v_mul_f32_e32 v62, v225, v224
	v_mul_f32_e32 v58, v227, v226
	v_mul_f32_e32 v228, v244, v52
	v_mul_f32_e32 v230, v244, v53
	v_mul_f32_e32 v232, v244, v54
	v_mul_f32_e32 v234, v244, v55
	v_mul_f32_e32 v229, v52, v48
	v_mul_f32_e32 v231, v53, v49
	v_mul_f32_e32 v233, v54, v50
	v_mul_f32_e32 v235, v55, v51
	v_exp_f32_e32 v228, v228
	v_exp_f32_e32 v230, v230
	v_exp_f32_e32 v232, v232
	v_exp_f32_e32 v234, v234
	v_fma_f32 v228, v228, v245, v245
	v_fma_f32 v230, v230, v245, v245
	v_fma_f32 v232, v232, v245, v245
	v_fma_f32 v234, v234, v245, v245
	v_rcp_f32_e32 v228, v228
	v_rcp_f32_e32 v230, v230
	v_rcp_f32_e32 v232, v232
	v_rcp_f32_e32 v234, v234
	v_mul_f32_e32 v52, v229, v228
	v_mul_f32_e32 v53, v231, v230
	v_mul_f32_e32 v54, v233, v232
	v_mul_f32_e32 v48, v235, v234
	v_cvt_pk_bf16_f32 v50, v60, v61
	v_cvt_pk_bf16_f32 v51, v62, v58
	v_cvt_pk_bf16_f32 v52, v52, v53
	s_nop 0
	v_cvt_pk_bf16_f32 v53, v54, v48
	v_lshl_add_u64 v[48:49], s[0:1], 0, v[168:169]
	v_lshl_add_u64 v[48:49], v[48:49], 0, v[144:145]
	global_store_dwordx4 v[48:49], v[50:53], off
	s_mov_b64 s[0:1], -1
	v_mul_f32_e32 v246, 0xbfb8aa3b, v150
	v_mul_f32_e32 v247, v150, v150
	v_rcp_f32_e32 v247, v247
	v_mul_f32_e32 v220, v246, v44
	v_mul_f32_e32 v222, v246, v45
	v_mul_f32_e32 v224, v246, v46
	v_mul_f32_e32 v226, v246, v47
	v_mul_f32_e32 v221, v44, v40
	v_mul_f32_e32 v223, v45, v41
	v_mul_f32_e32 v225, v46, v42
	v_mul_f32_e32 v227, v47, v43
	v_exp_f32_e32 v220, v220
	v_exp_f32_e32 v222, v222
	v_exp_f32_e32 v224, v224
	v_exp_f32_e32 v226, v226
	v_fma_f32 v220, v220, v247, v247
	v_fma_f32 v222, v222, v247, v247
	v_fma_f32 v224, v224, v247, v247
	v_fma_f32 v226, v226, v247, v247
	v_rcp_f32_e32 v220, v220
	v_rcp_f32_e32 v222, v222
	v_rcp_f32_e32 v224, v224
	v_rcp_f32_e32 v226, v226
	v_mul_f32_e32 v44, v221, v220
	v_mul_f32_e32 v45, v223, v222
	v_mul_f32_e32 v46, v225, v224
	v_mul_f32_e32 v42, v227, v226
	v_mul_f32_e32 v228, v246, v36
	v_mul_f32_e32 v230, v246, v37
	v_mul_f32_e32 v232, v246, v38
	v_mul_f32_e32 v234, v246, v39
	v_mul_f32_e32 v229, v36, v32
	v_mul_f32_e32 v231, v37, v33
	v_mul_f32_e32 v233, v38, v34
	v_mul_f32_e32 v235, v39, v35
	v_exp_f32_e32 v228, v228
	v_exp_f32_e32 v230, v230
	v_exp_f32_e32 v232, v232
	v_exp_f32_e32 v234, v234
	v_fma_f32 v228, v228, v247, v247
	v_fma_f32 v230, v230, v247, v247
	v_fma_f32 v232, v232, v247, v247
	v_fma_f32 v234, v234, v247, v247
	v_rcp_f32_e32 v228, v228
	v_rcp_f32_e32 v230, v230
	v_rcp_f32_e32 v232, v232
	v_rcp_f32_e32 v234, v234
	v_mul_f32_e32 v36, v229, v228
	v_mul_f32_e32 v37, v231, v230
	v_mul_f32_e32 v38, v233, v232
	v_mul_f32_e32 v35, v235, v234
	v_cvt_pk_bf16_f32 v32, v44, v45
	v_cvt_pk_bf16_f32 v33, v46, v42
	v_cvt_pk_bf16_f32 v34, v36, v37
	v_cvt_pk_bf16_f32 v35, v38, v35
	global_store_dwordx4 v[48:49], v[32:35], off offset:1024
	s_nop 1
	v_mul_f32_e32 v248, 0xbfb8aa3b, v148
	v_mul_f32_e32 v249, v148, v148
	v_rcp_f32_e32 v249, v249
	v_mul_f32_e32 v220, v248, v28
	v_mul_f32_e32 v222, v248, v29
	v_mul_f32_e32 v224, v248, v30
	v_mul_f32_e32 v226, v248, v31
	v_mul_f32_e32 v221, v28, v24
	v_mul_f32_e32 v223, v29, v25
	v_mul_f32_e32 v225, v30, v26
	v_mul_f32_e32 v227, v31, v27
	v_exp_f32_e32 v220, v220
	v_exp_f32_e32 v222, v222
	v_exp_f32_e32 v224, v224
	v_exp_f32_e32 v226, v226
	v_fma_f32 v220, v220, v249, v249
	v_fma_f32 v222, v222, v249, v249
	v_fma_f32 v224, v224, v249, v249
	v_fma_f32 v226, v226, v249, v249
	v_rcp_f32_e32 v220, v220
	v_rcp_f32_e32 v222, v222
	v_rcp_f32_e32 v224, v224
	v_rcp_f32_e32 v226, v226
	v_mul_f32_e32 v28, v221, v220
	v_mul_f32_e32 v29, v223, v222
	v_mul_f32_e32 v30, v225, v224
	v_mul_f32_e32 v26, v227, v226
	v_mul_f32_e32 v228, v248, v20
	v_mul_f32_e32 v230, v248, v21
	v_mul_f32_e32 v232, v248, v22
	v_mul_f32_e32 v234, v248, v23
	v_mul_f32_e32 v229, v20, v16
	v_mul_f32_e32 v231, v21, v17
	v_mul_f32_e32 v233, v22, v18
	v_mul_f32_e32 v235, v23, v19
	v_exp_f32_e32 v228, v228
	v_exp_f32_e32 v230, v230
	v_exp_f32_e32 v232, v232
	v_exp_f32_e32 v234, v234
	v_fma_f32 v228, v228, v249, v249
	v_fma_f32 v230, v230, v249, v249
	v_fma_f32 v232, v232, v249, v249
	v_fma_f32 v234, v234, v249, v249
	v_rcp_f32_e32 v228, v228
	v_rcp_f32_e32 v230, v230
	v_rcp_f32_e32 v232, v232
	v_rcp_f32_e32 v234, v234
	v_mul_f32_e32 v20, v229, v228
	v_mul_f32_e32 v21, v231, v230
	v_mul_f32_e32 v22, v233, v232
	v_mul_f32_e32 v19, v235, v234
	v_cvt_pk_bf16_f32 v16, v28, v29
	v_cvt_pk_bf16_f32 v17, v30, v26
	v_cvt_pk_bf16_f32 v18, v20, v21
	v_cvt_pk_bf16_f32 v19, v22, v19
	global_store_dwordx4 v[48:49], v[16:19], off offset:2048
	s_nop 1
	v_mul_f32_e32 v250, 0xbfb8aa3b, v146
	v_mul_f32_e32 v251, v146, v146
	v_rcp_f32_e32 v251, v251
	v_mul_f32_e32 v220, v250, v12
	v_mul_f32_e32 v222, v250, v13
	v_mul_f32_e32 v224, v250, v14
	v_mul_f32_e32 v226, v250, v15
	v_mul_f32_e32 v221, v12, v8
	v_mul_f32_e32 v223, v13, v9
	v_mul_f32_e32 v225, v14, v10
	v_mul_f32_e32 v227, v15, v11
	v_exp_f32_e32 v220, v220
	v_exp_f32_e32 v222, v222
	v_exp_f32_e32 v224, v224
	v_exp_f32_e32 v226, v226
	v_fma_f32 v220, v220, v251, v251
	v_fma_f32 v222, v222, v251, v251
	v_fma_f32 v224, v224, v251, v251
	v_fma_f32 v226, v226, v251, v251
	v_rcp_f32_e32 v220, v220
	v_rcp_f32_e32 v222, v222
	v_rcp_f32_e32 v224, v224
	v_rcp_f32_e32 v226, v226
	v_mul_f32_e32 v12, v221, v220
	v_mul_f32_e32 v13, v223, v222
	v_mul_f32_e32 v14, v225, v224
	v_mul_f32_e32 v10, v227, v226
	v_mul_f32_e32 v228, v250, v4
	v_mul_f32_e32 v230, v250, v5
	v_mul_f32_e32 v232, v250, v6
	v_mul_f32_e32 v234, v250, v7
	v_mul_f32_e32 v229, v4, v0
	v_mul_f32_e32 v231, v5, v1
	v_mul_f32_e32 v233, v6, v2
	v_mul_f32_e32 v235, v7, v3
	v_exp_f32_e32 v228, v228
	v_exp_f32_e32 v230, v230
	v_exp_f32_e32 v232, v232
	v_exp_f32_e32 v234, v234
	v_fma_f32 v228, v228, v251, v251
	v_fma_f32 v230, v230, v251, v251
	v_fma_f32 v232, v232, v251, v251
	v_fma_f32 v234, v234, v251, v251
	v_rcp_f32_e32 v228, v228
	v_rcp_f32_e32 v230, v230
	v_rcp_f32_e32 v232, v232
	v_rcp_f32_e32 v234, v234
	v_mul_f32_e32 v4, v229, v228
	v_mul_f32_e32 v5, v231, v230
	v_mul_f32_e32 v6, v233, v232
	v_mul_f32_e32 v3, v235, v234
	v_cvt_pk_bf16_f32 v0, v12, v13
	v_cvt_pk_bf16_f32 v1, v14, v10
	v_cvt_pk_bf16_f32 v2, v4, v5
	v_cvt_pk_bf16_f32 v3, v6, v3
	global_store_dwordx4 v[48:49], v[0:3], off offset:3072
	s_cbranch_vccnz .LBB0_1061
	s_andn2_b64 vcc, exec, s[4:5]
	s_cbranch_vccnz .LBB0_1060
	s_barrier
	s_branch .LBB0_1060
	s_nop 0
	s_nop 0
	s_nop 0
	s_nop 0
	s_nop 0
	s_nop 0
	s_nop 0
	s_nop 0
	s_nop 0
	s_nop 0
	s_nop 0
	s_nop 0
	s_nop 0
	s_nop 0
	s_nop 0
	s_nop 0
	s_nop 0
	s_nop 0
	s_nop 0
	s_nop 0
	s_nop 0
	s_nop 0
	s_nop 0
	s_nop 0
	s_nop 0
	s_nop 0
	s_nop 0
	s_nop 0
	s_nop 0
	s_nop 0
	s_nop 0
	s_nop 0
	s_nop 0
	s_nop 0
	s_nop 0
	s_nop 0
	s_nop 0
	s_nop 0
	s_nop 0
	s_nop 0
	s_nop 0
	s_nop 0
	s_nop 0
	s_nop 0
	s_nop 0
	s_nop 0
	s_nop 0
	s_nop 0
	s_nop 0
	s_nop 0
	s_nop 0
	s_nop 0
	s_nop 0
	s_nop 0
	s_nop 0
	s_nop 0
	s_nop 0
	s_nop 0
	s_nop 0
	s_nop 0
	s_nop 0
	s_nop 0
	s_nop 0
	s_nop 0
	s_nop 0
	s_nop 0
	s_nop 0
	s_nop 0
	s_nop 0
	s_nop 0
	s_nop 0
	s_nop 0
	s_nop 0
	s_nop 0
	s_nop 0
	s_nop 0
	s_nop 0
	s_nop 0
	s_nop 0
	s_nop 0
	s_nop 0
	s_nop 0
	s_nop 0
	s_nop 0
	s_nop 0
	s_nop 0
	s_nop 0
	s_nop 0
	s_nop 0
	s_nop 0
	s_nop 0
	s_nop 0
	s_nop 0
	s_nop 0
	s_nop 0
